# hot diff-attention loops: the 11-deep v_pk_add_f32 chain at the loop latch (in the PV MFMA shadow) split into two interleaved scalar v_add_f32 chains (bit-identical)
# speedup vs baseline: 1.0087x; 1.0039x over previous
.LBB0_741:
	v_add_f32_e32 v76, 0, v165
	v_add_f32_e32 v76, v183, v76
	v_add_f32_e32 v76, v96, v76
	v_add_f32_e32 v76, v97, v76
	v_add_f32_e32 v76, v98, v76
	v_add_f32_e32 v76, v99, v76
	v_add_f32_e32 v76, v100, v76
	v_add_f32_e32 v76, v101, v76
	v_add_f32_e32 v76, v102, v76
	v_add_f32_e32 v76, v103, v76
	v_add_f32_e32 v76, v104, v76
	v_add_f32_e32 v76, v105, v76
	v_add_f32_e32 v76, v106, v76
	v_add_f32_e32 v76, v107, v76
	v_add_f32_e32 v76, v108, v76
	v_add_f32_e32 v76, v109, v76
	v_add_f32_e32 v76, v184, v76
	v_add_f32_e32 v76, v185, v76
	v_add_f32_e32 v76, v186, v76
	v_add_f32_e32 v76, v187, v76
	v_add_f32_e32 v76, v188, v76
	v_add_f32_e32 v77, v189, v76
	v_add_f32_e32 v76, 0, v110
	v_add_f32_e32 v76, v111, v76
	v_add_f32_e32 v76, v112, v76
	v_add_f32_e32 v76, v113, v76
	v_add_f32_e32 v76, v114, v76
	v_add_f32_e32 v76, v115, v76
	v_add_f32_e32 v76, v116, v76
	v_add_f32_e32 v76, v117, v76
	v_add_f32_e32 v76, v118, v76
	v_add_f32_e32 v76, v119, v76
	v_add_f32_e32 v76, v120, v76
	v_add_f32_e32 v76, v121, v76
	v_add_f32_e32 v76, v122, v76
	v_add_f32_e32 v76, v123, v76
	v_add_f32_e32 v76, v124, v76
	v_add_f32_e32 v76, v125, v76
	v_add_f32_e32 v76, v237, v76
	v_add_f32_e32 v76, v238, v76
	v_add_f32_e32 v76, v239, v76
	v_add_f32_e32 v76, v240, v76
	v_add_f32_e32 v76, v241, v76
	v_add_f32_e32 v76, v242, v76
	v_add_f32_e32 v66, v66, v76
	v_add_f32_e32 v67, v67, v77
	s_mov_b64 s[0:1], 0x80
	v_add_f32_e32 v64, v64, v66
	v_add_f32_e32 v65, v65, v67
	s_add_i32 s5, s5, 1
	v_add_f32_e32 v64, v86, v64
	v_add_f32_e32 v65, v87, v65
	s_add_i32 s4, s4, 64
	v_add_f32_e32 v64, v84, v64
	v_add_f32_e32 v65, v85, v65
	v_lshl_add_u64 v[166:167], v[166:167], 0, s[0:1]
	v_add_f32_e32 v64, v82, v64
	v_add_f32_e32 v65, v83, v65
	v_lshl_add_u64 v[168:169], v[168:169], 0, s[0:1]
	v_add_f32_e32 v64, v80, v64
	v_add_f32_e32 v65, v81, v65
	s_mov_b64 s[0:1], 0x2c000
	v_add_f32_e32 v64, v72, v64
	v_add_f32_e32 v65, v73, v65
	v_lshl_add_u64 v[170:171], v[170:171], 0, s[0:1]
	v_add_f32_e32 v64, v74, v64
	v_add_f32_e32 v65, v75, v65
	s_cmp_lg_u32 s5, 4
	v_add_f32_e32 v64, v70, v64
	v_add_f32_e32 v65, v71, v65
	v_lshl_add_u64 v[172:173], v[172:173], 0, s[0:1]
	v_add_f32_e32 v64, v68, v64
	v_add_f32_e32 v65, v69, v65
	s_waitcnt lgkmcnt(0)
	v_add_f32_e32 v160, v160, v64
	v_add_f32_e32 v161, v161, v65
	s_barrier
	s_cbranch_scc0 .LBB0_746

.LBB0_769:
	v_add_f32_e32 v76, 0, v175
	v_add_f32_e32 v76, v181, v76
	v_add_f32_e32 v76, v96, v76
	v_add_f32_e32 v76, v97, v76
	v_add_f32_e32 v76, v98, v76
	v_add_f32_e32 v76, v99, v76
	v_add_f32_e32 v76, v100, v76
	v_add_f32_e32 v76, v101, v76
	v_add_f32_e32 v76, v102, v76
	v_add_f32_e32 v76, v103, v76
	v_add_f32_e32 v76, v104, v76
	v_add_f32_e32 v76, v105, v76
	v_add_f32_e32 v76, v106, v76
	v_add_f32_e32 v76, v107, v76
	v_add_f32_e32 v76, v108, v76
	v_add_f32_e32 v76, v109, v76
	v_add_f32_e32 v76, v183, v76
	v_add_f32_e32 v76, v184, v76
	v_add_f32_e32 v76, v185, v76
	v_add_f32_e32 v76, v186, v76
	v_add_f32_e32 v76, v187, v76
	v_add_f32_e32 v77, v188, v76
	v_add_f32_e32 v76, 0, v110
	v_add_f32_e32 v76, v111, v76
	v_add_f32_e32 v76, v112, v76
	v_add_f32_e32 v76, v113, v76
	v_add_f32_e32 v76, v114, v76
	v_add_f32_e32 v76, v115, v76
	v_add_f32_e32 v76, v116, v76
	v_add_f32_e32 v76, v117, v76
	v_add_f32_e32 v76, v118, v76
	v_add_f32_e32 v76, v119, v76
	v_add_f32_e32 v76, v120, v76
	v_add_f32_e32 v76, v121, v76
	v_add_f32_e32 v76, v122, v76
	v_add_f32_e32 v76, v123, v76
	v_add_f32_e32 v76, v124, v76
	v_add_f32_e32 v76, v125, v76
	v_add_f32_e32 v76, v189, v76
	v_add_f32_e32 v76, v237, v76
	v_add_f32_e32 v76, v238, v76
	v_add_f32_e32 v76, v239, v76
	v_add_f32_e32 v76, v240, v76
	v_add_f32_e32 v76, v241, v76
	v_add_f32_e32 v66, v66, v76
	v_add_f32_e32 v67, v67, v77
	s_add_i32 s4, s4, 64
	v_add_f32_e32 v64, v64, v66
	v_add_f32_e32 v65, v65, v67
	s_mov_b64 s[0:1], 0x80
	v_add_f32_e32 v64, v86, v64
	v_add_f32_e32 v65, v87, v65
	s_add_i32 s5, s5, 1
	v_add_f32_e32 v64, v84, v64
	v_add_f32_e32 v65, v85, v65
	v_lshl_add_u64 v[166:167], v[166:167], 0, s[0:1]
	v_add_f32_e32 v64, v82, v64
	v_add_f32_e32 v65, v83, v65
	s_cmpk_lg_i32 s4, 0x1100
	v_add_f32_e32 v64, v80, v64
	v_add_f32_e32 v65, v81, v65
	v_lshl_add_u64 v[168:169], v[168:169], 0, s[0:1]
	v_add_f32_e32 v64, v72, v64
	v_add_f32_e32 v65, v73, v65
	s_waitcnt lgkmcnt(0)
	v_add_f32_e32 v64, v74, v64
	v_add_f32_e32 v65, v75, v65
	s_barrier
	v_add_f32_e32 v64, v70, v64
	v_add_f32_e32 v65, v71, v65
	s_nop 0
	v_add_f32_e32 v64, v68, v64
	v_add_f32_e32 v65, v69, v65
	s_nop 0
	v_add_f32_e32 v160, v160, v64
	v_add_f32_e32 v161, v161, v65
	s_cbranch_scc0 .LBB0_774
